# v44 plus gMLP unit epilogue loads prefetched (frees hyena-side time) and scan-shadow conversion budget raised to 3 iterations
# speedup vs baseline: 1.0061x; 1.0038x over previous
; #define LAS __attribute__((address_space(3)))
; __device__ __forceinline__ void convert_layer_static(const PT& a, LAS unsigned char* lds, int l, int gw, int NGW, int wave, int lane, int r_end = IT_LAYER) {
;     for (int r = 2 * gw; r < r_end; r += 2 * NGW) cv_pair(a, lds, l, r, wave, lane);
; }
; __device__ __forceinline__ void prologue_a(const PT& a, LAS unsigned char* lds) {
;     ...
;     convert_layer_static(a, lds, 0, gw, NGW, wave, lane);
;     for (int cl_ = 1; cl_ < DEPTH; ++cl_) convert_layer_static(a, lds, cl_, gw, NGW, wave, lane, CV_PRO_ITEMS);
.LBB0_110:
	s_or_b64 exec, exec, s[12:13]
	v_lshl_add_u32 v2, v74, 2, v115
	v_add_u32_e32 v3, v115, v113
	s_mov_b32 s13, 0
	v_lshl_add_u32 v113, v67, 2, v3
	v_lshl_add_u32 v115, v69, 2, v3
	v_lshl_add_u32 v117, v97, 2, v3
	v_lshl_add_u32 v119, v99, 2, v3
	s_mov_b32 s18, 1
	s_lshl_b32 s42, s17, 5
	s_movk_i32 s43, 0x393f
	s_movk_i32 s44, 0x453f
	s_movk_i32 s45, 0x4d3f
	s_movk_i32 s46, 0x793f
	s_movk_i32 s47, 0x15ff
	s_movk_i32 s48, 0xba3
	s_movk_i32 s49, 0x1600
	s_movk_i32 s50, 0x3ff
	v_mov_b32_e32 v79, 0
	s_mov_b64 s[20:21], 0xea00000
	s_mov_b32 s51, 0x478bbced
	s_movk_i32 s52, 0x9f
	s_movk_i32 s53, 0x109
	v_add_u32_e32 v121, v2, v121
	v_lshlrev_b64 v[76:77], 1, v[76:77]
	s_mov_b32 s54, 0x573f
	v_readlane_b32 s100, v252, 4
	s_cmp_eq_u32 s100, 0x100
	s_cselect_b32 s54, s54, 0x8f3f
	v_mov_b32_e32 v123, 0xea00
	v_mov_b32_e32 v125, 5
	v_mov_b32_e32 v128, 0x23a40
	v_mov_b32_e32 v129, 0x23a38
	v_mov_b32_e32 v130, 6
	v_mov_b32_e32 v131, 0x80
	v_mov_b32_e32 v132, 0x23a20
	v_mov_b32_e32 v133, 0x23a18
	v_mov_b32_e32 v134, 0x23a10
	s_branch .LBB0_112

;     __device__ __forceinline__ const float* in(int i) const { return (const float*)(const GAS float*)raw(i); }
;     __device__ __forceinline__ unsigned char* ws() const { return (unsigned char*)(GAS unsigned char*)raw(N_INPUTS + 1); }
; __device__ __forceinline__ CvItem cv_decode(const PT& a, int l, int r) {
;     unsigned char* ws = a.ws(); CvItem it;
;     if (r < IT_WIN) { const int kb = r / 458, nb = r % 458, n0 = nb * 32;
;         int drow; if (n0 < 2048) drow = n0; else if (n0 < 5120) drow = NIN_MAIN + (n0 - 2048); else if (n0 < 8512) drow = 2048 + (n0 - 5120); else drow = 5632 + (n0 - 8512);
;         it = CvItem{a.in(I_W_IN) + (size_t)l * D * NIN, NIN, kb * 64, n0, (bf16_t*)(ws + WS_WIN + l * WIN_L), D, drow, a.in(I_NORM_MIX_G) + l * D}; return it; }
;     r -= IT_WIN;
;     if (r < 3 * IT_BR) { const int br = r / IT_BR; r -= br * IT_BR; const int kb = r / 64, nb = r % 64;
;         it = CvItem{a.in(br == 0 ? I_W_BR_A : (br == 1 ? I_W_BR_B : I_W_BR_C)) + (size_t)l * 1024 * D, D, kb * 64, nb * 32, (bf16_t*)(ws + WS_WBR + l * WBR_L) + (size_t)br * D * 1024, 1024, nb * 32, nullptr}; return it; }
;     r -= 3 * IT_BR;
;     if (r < IT_OUT) { const int kb = r / 64, nb = r % 64;
;         it = CvItem{a.in(I_W_OUT) + (size_t)l * D * D, D, kb * 64, nb * 32, (bf16_t*)(ws + WS_WOUT + l * WOUT_L), D, nb * 32, nullptr}; return it; }
;     r -= IT_OUT;
;     if (r < 2 * IT_GU) { const int up = r / IT_GU; r -= up * IT_GU; const int kb = r / 176, nb = r % 176, n0 = nb * 32;
;         it = CvItem{a.in(up ? I_W_FFN_UP : I_W_FFN_GATE) + (size_t)l * D * DFF, DFF, kb * 64, n0, (bf16_t*)(ws + WS_WGU + l * WGU_L), D, 256 * (n0 / 128) + (n0 % 128) + 128 * up, a.in(I_NORM_FFN_G) + l * D}; return it; }
;     r -= 2 * IT_GU;
;     { const int kb = r / 64, nb = r % 64;
;       it = CvItem{a.in(I_W_FFN_DOWN) + (size_t)l * DFF * D, D, kb * 64, nb * 32, (bf16_t*)(ws + WS_WDN + l * WDN_L), DFF, nb * 32, nullptr}; }
;     for (int it = 0; it < budget; ++it) {
;         unsigned r = 0; if (lane == 0) r = __hip_atomic_fetch_add(ctr, 2u, __ATOMIC_RELAXED, __HIP_MEMORY_SCOPE_AGENT);
;         r = (unsigned)__builtin_amdgcn_readfirstlane((int)r) + (unsigned)CV_PRO_ITEMS;
;         if (r >= (unsigned)IT_LAYER) break;
;         cv_pair(a, lds, l, (int)r, wave, lane);
.LcvqA_1381:
	s_mov_b32 s24, s100
	s_add_u32 s100, s100, 0xc00
	s_add_i32 s24, s24, 0xffffc800
	s_cmp_lt_u32 s24, 0xffff70c0
	s_mov_b64 s[2:3], -1
	s_cbranch_scc1 .LcvqA_1380
	v_mov_b32_e32 v2, 0x23a60
	s_add_i32 s15, s24, 0x8f40
	v_add_u32_e32 v2, 0, v2
	ds_read_b64 v[2:3], v2
	s_cmpk_gt_u32 s15, 0x393f
	s_waitcnt lgkmcnt(0)
	v_readfirstlane_b32 s20, v3
	v_readfirstlane_b32 s21, v2
	s_cbranch_scc0 .LcvqA_1399
	s_cmpk_gt_u32 s15, 0x453f
	s_cbranch_scc0 .LcvqA_1396
	s_cmpk_gt_u32 s15, 0x4d3f
	s_mov_b64 s[18:19], -1
	s_cbranch_scc0 .LcvqA_1393
	s_cmpk_gt_u32 s15, 0x793f
	s_cbranch_scc0 .LcvqA_1391
	v_mov_b32_e32 v2, 0x23a48
	s_and_b32 s2, s15, 0x7fffffc0
	v_add_u32_e32 v2, 0, v2
	ds_read_b64 v[2:3], v2
	s_add_i32 s14, s2, 0xffff86c0
	s_waitcnt lgkmcnt(0)
	v_readfirstlane_b32 s3, v2
	v_readfirstlane_b32 s2, v3
	s_add_u32 s30, s3, s34
	s_addc_u32 s31, s2, s33
	s_lshl_b32 s2, s15, 5
	s_and_b32 s25, s2, 0x7e0
	s_add_u32 s2, s21, s50
	s_addc_u32 s3, s20, s35
	s_add_u32 s12, s2, 0x1ea00000
	s_addc_u32 s13, s3, 0
	s_mov_b64 s[2:3], 0

; #define LAS __attribute__((address_space(3)))
; __device__ __forceinline__ unsigned f2bf(float f) { return pk2(f, f) & 0xffffu; }
;     __device__ __forceinline__ const float* in(int i) const { return (const float*)(const GAS float*)raw(i); }
;     __device__ __forceinline__ unsigned char* ws() const { return (unsigned char*)(GAS unsigned char*)raw(N_INPUTS + 1); }
; __device__ __forceinline__ void gmlp_unit2(const PT& a, int l, int u, LAS unsigned char* lds) {
;     ...
;     const int pt_ = wave & 3, dt0 = (wave >> 2) * 2, n = lane & 31, hh = lane >> 5;
;     const bf16_t* wrow = (const bf16_t*)(ws + WS_GWS) + (((size_t)l * AG + g) * 128 + pt_ * 32 + n) * 128 + 8 * hh;
;     f32x16 acc0, acc1;
; #pragma unroll
;     for (int r = 0; r < 16; ++r) { acc0[r] = 0.f; acc1[r] = 0.f; }
;     const LAS unsigned char* b0p = lds + (dt0 * 32 + n) * GM_PITCH + 16 * hh;
; #pragma unroll
;     for (int ks = 0; ks < 8; ++ks) { const bf16x8 af = *(const bf16x8*)(wrow + ks * 16);
;         const bf16x8 bf0 = *(const LAS bf16x8*)(b0p + ks * 32), bf1 = *(const LAS bf16x8*)(b0p + 32 * GM_PITCH + ks * 32);
;         acc0 = __builtin_amdgcn_mfma_f32_32x32x16_bf16(af, bf0, acc0, 0, 0, 0);
;         acc1 = __builtin_amdgcn_mfma_f32_32x32x16_bf16(af, bf1, acc1, 0, 0, 0); }
;     const float* bs = a.in(I_GM_BS) + ((size_t)l * AG + g) * 128;
;     bf16_t* YA = (bf16_t*)(ws + WS_YA);
; #pragma unroll
;     for (int r = 0; r < 16; ++r) { const int p = pt_ * 32 + (r & 3) + 8 * (r >> 2) + 4 * hh; const float bb = bs[p];
;         const size_t o = (size_t)(tok0 + p) * 2048 + g * 128 + dt0 * 32 + n;
;         const float u0 = bf2f(PA[o]), u1 = bf2f(PA[o + 32]);
;         const size_t oy = (size_t)(tok0 + p) * 1024 + g * 128 + dt0 * 32 + n;
;         YA[oy] = (bf16_t)f2bf(u0 * (acc0[r] + bb)); YA[oy + 32] = (bf16_t)f2bf(u1 * (acc1[r] + bb)); }
.LBB0_1207:
	s_or_b64 exec, exec, s[0:1]
	v_readlane_b32 s10, v254, 53
	s_lshr_b32 s0, s19, 1
	s_or_b32 s10, s18, s56
	s_and_b32 s7, s0, 0x60
	v_and_b32_e32 v48, 31, v1
	s_or_b32 s0, s10, s7
	v_or_b32_e32 v2, s0, v48
	v_bfe_u32 v1, v1, 5, 1
	v_lshlrev_b32_e32 v132, 8, v2
	v_lshl_add_u64 v[2:3], s[4:5], 0, v[132:133]
	v_lshlrev_b32_e32 v132, 4, v1
	v_lshl_add_u64 v[2:3], v[2:3], 0, v[132:133]
	s_mov_b64 s[0:1], 0x6b870000
	v_lshl_add_u64 v[46:47], v[2:3], 0, s[0:1]
	s_ashr_i32 s0, s19, 2
	s_and_b32 s6, s0, 0xffffffc0
	v_or_b32_e32 v4, s6, v48
	s_movk_i32 s0, 0x110
	v_mul_lo_u32 v4, v4, s0
	s_mov_b32 s0, 0x6b870000
	v_add_co_u32_e32 v2, vcc, s0, v2
	s_waitcnt lgkmcnt(0)
	s_nop 0
	v_addc_co_u32_e32 v3, vcc, 0, v3, vcc
	s_barrier
	v_add3_u32 v49, 0, v4, v132
	global_load_dwordx4 v[2:5], v[2:3], off
	ds_read_b128 v[6:9], v49 offset:8704
	ds_read_b128 v[10:13], v49
	ds_read_b128 v[34:37], v49 offset:32
	global_load_dwordx4 v[38:41], v[46:47], off offset:32
	ds_read_b128 v[42:45], v49 offset:8736
	v_readlane_b32 s11, v254, 54
	s_mov_b32 s1, s11
	v_writelane_b32 v254, s0, 53
	v_lshlrev_b32_e32 v132, 1, v48
	s_waitcnt vmcnt(1) lgkmcnt(2)
	v_mfma_f32_32x32x16_bf16 v[18:33], v[2:5], v[10:13], 0
	v_writelane_b32 v254, s1, 54
	s_lshl_b64 s[0:1], s[10:11], 2
	s_waitcnt vmcnt(0) lgkmcnt(1)
	v_mfma_f32_32x32x16_bf16 v[18:33], v[38:41], v[34:37], v[18:33]
	global_load_dwordx4 v[34:37], v[46:47], off offset:64
	v_mfma_f32_32x32x16_bf16 v[2:17], v[2:5], v[6:9], 0
	s_waitcnt lgkmcnt(0)
	v_mfma_f32_32x32x16_bf16 v[2:17], v[38:41], v[42:45], v[2:17]
	ds_read_b128 v[38:41], v49 offset:64
	ds_read_b128 v[42:45], v49 offset:8768
	s_waitcnt vmcnt(0) lgkmcnt(1)
	v_mfma_f32_32x32x16_bf16 v[18:33], v[34:37], v[38:41], v[18:33]
	s_waitcnt lgkmcnt(0)
	v_mfma_f32_32x32x16_bf16 v[2:17], v[34:37], v[42:45], v[2:17]
	global_load_dwordx4 v[34:37], v[46:47], off offset:96
	ds_read_b128 v[38:41], v49 offset:96
	ds_read_b128 v[42:45], v49 offset:8800
	s_waitcnt vmcnt(0) lgkmcnt(1)
	v_mfma_f32_32x32x16_bf16 v[18:33], v[34:37], v[38:41], v[18:33]
	s_waitcnt lgkmcnt(0)
	v_mfma_f32_32x32x16_bf16 v[2:17], v[34:37], v[42:45], v[2:17]
	global_load_dwordx4 v[34:37], v[46:47], off offset:128
	ds_read_b128 v[38:41], v49 offset:128
	ds_read_b128 v[42:45], v49 offset:8832
	s_waitcnt vmcnt(0) lgkmcnt(1)
	v_mfma_f32_32x32x16_bf16 v[18:33], v[34:37], v[38:41], v[18:33]
	s_waitcnt lgkmcnt(0)
	v_mfma_f32_32x32x16_bf16 v[2:17], v[34:37], v[42:45], v[2:17]
	global_load_dwordx4 v[34:37], v[46:47], off offset:160
	ds_read_b128 v[38:41], v49 offset:160
	ds_read_b128 v[42:45], v49 offset:8864
	s_waitcnt vmcnt(0) lgkmcnt(1)
	v_mfma_f32_32x32x16_bf16 v[18:33], v[34:37], v[38:41], v[18:33]
	s_waitcnt lgkmcnt(0)
	v_mfma_f32_32x32x16_bf16 v[2:17], v[34:37], v[42:45], v[2:17]
	global_load_dwordx4 v[34:37], v[46:47], off offset:192
	ds_read_b128 v[38:41], v49 offset:192
	ds_read_b128 v[42:45], v49 offset:8896
	s_waitcnt vmcnt(0) lgkmcnt(1)
	v_mfma_f32_32x32x16_bf16 v[18:33], v[34:37], v[38:41], v[18:33]
	s_waitcnt lgkmcnt(0)
	v_mfma_f32_32x32x16_bf16 v[2:17], v[34:37], v[42:45], v[2:17]
	global_load_dwordx4 v[34:37], v[46:47], off offset:224
	ds_read_b128 v[38:41], v49 offset:224
	ds_read_b128 v[42:45], v49 offset:8928
	s_waitcnt vmcnt(0) lgkmcnt(1)
	v_mfma_f32_32x32x16_bf16 v[18:33], v[34:37], v[38:41], v[18:33]
	s_waitcnt lgkmcnt(0)
	v_mfma_f32_32x32x16_bf16 v[2:17], v[34:37], v[42:45], v[2:17]
	v_mov_b32_e32 v34, 0x23930
	v_lshl_or_b32 v42, v1, 2, s7
	v_add_u32_e32 v34, 0, v34
	ds_read_b64 v[34:35], v34
	v_lshlrev_b32_e32 v1, 2, v42
	v_or_b32_e32 v42, s3, v42
	v_ashrrev_i32_e32 v43, 31, v42
	v_lshlrev_b64 v[44:45], 12, v[42:43]
	s_waitcnt lgkmcnt(0)
	v_readfirstlane_b32 s9, v34
	v_readfirstlane_b32 s8, v35
	s_add_u32 s0, s9, s0
	s_addc_u32 s1, s8, s1
	s_ashr_i32 s7, s6, 31
	s_lshl_b32 s10, s18, 1
	s_add_u32 s8, s16, s10
	s_addc_u32 s9, s17, 0
	s_lshl_b64 s[6:7], s[6:7], 1
	s_add_u32 s8, s8, s6
	s_addc_u32 s9, s9, s7
	s_add_u32 s4, s4, s10
	s_addc_u32 s5, s5, 0
	s_add_u32 s4, s4, s6
	v_lshl_add_u64 v[40:41], s[8:9], 0, v[132:133]
	s_addc_u32 s5, s5, s7
	v_lshl_add_u64 v[34:35], s[4:5], 0, v[132:133]
	s_mov_b64 s[4:5], 0x5ad00000
	v_lshl_add_u64 v[44:45], v[40:41], 0, v[44:45]
	v_lshl_add_u64 v[38:39], v[34:35], 0, s[4:5]
	v_mov_b64_e32 v[108:109], v[44:45]
	global_load_dwordx4 v[92:95], v1, s[0:1]
	global_load_dwordx4 v[96:99], v1, s[0:1] offset:32
	global_load_dwordx4 v[100:103], v1, s[0:1] offset:64
	global_load_dwordx4 v[104:107], v1, s[0:1] offset:96
	global_load_ushort v60, v[108:109], off
	global_load_ushort v61, v[108:109], off offset:64
	s_mov_b64 s[100:101], 0x1000
	v_lshl_add_u64 v[110:111], v[108:109], 0, s[100:101]
	global_load_ushort v62, v[110:111], off
	global_load_ushort v63, v[110:111], off offset:64
	s_mov_b64 s[100:101], 0x2000
	v_lshl_add_u64 v[110:111], v[108:109], 0, s[100:101]
	global_load_ushort v64, v[110:111], off
	global_load_ushort v65, v[110:111], off offset:64
	s_mov_b64 s[100:101], 0x3000
	v_lshl_add_u64 v[110:111], v[108:109], 0, s[100:101]
	global_load_ushort v66, v[110:111], off
	global_load_ushort v67, v[110:111], off offset:64
	s_mov_b64 s[100:101], 0x8000
	v_lshl_add_u64 v[110:111], v[108:109], 0, s[100:101]
	global_load_ushort v68, v[110:111], off
	global_load_ushort v69, v[110:111], off offset:64
	s_mov_b64 s[100:101], 0x9000
	v_lshl_add_u64 v[110:111], v[108:109], 0, s[100:101]
	global_load_ushort v70, v[110:111], off
	global_load_ushort v71, v[110:111], off offset:64
	s_mov_b64 s[100:101], 0xa000
	v_lshl_add_u64 v[110:111], v[108:109], 0, s[100:101]
	global_load_ushort v72, v[110:111], off
	global_load_ushort v73, v[110:111], off offset:64
	s_mov_b64 s[100:101], 0xb000
; __device__ __forceinline__ unsigned f2bf(float f) { return pk2(f, f) & 0xffffu; }
; __device__ __forceinline__ void gmlp_unit2(const PT& a, int l, int u, LAS unsigned char* lds) {
;     ...
; #pragma unroll
;     for (int r = 0; r < 16; ++r) { const int p = pt_ * 32 + (r & 3) + 8 * (r >> 2) + 4 * hh; const float bb = bs[p];
;         const size_t o = (size_t)(tok0 + p) * 2048 + g * 128 + dt0 * 32 + n;
;         const float u0 = bf2f(PA[o]), u1 = bf2f(PA[o + 32]);
;         const size_t oy = (size_t)(tok0 + p) * 1024 + g * 128 + dt0 * 32 + n;
;         YA[oy] = (bf16_t)f2bf(u0 * (acc0[r] + bb)); YA[oy + 32] = (bf16_t)f2bf(u1 * (acc1[r] + bb)); }
	v_lshl_add_u64 v[110:111], v[108:109], 0, s[100:101]
	global_load_ushort v74, v[110:111], off
	global_load_ushort v75, v[110:111], off offset:64
	s_mov_b64 s[100:101], 0x10000
	v_lshl_add_u64 v[110:111], v[108:109], 0, s[100:101]
	global_load_ushort v76, v[110:111], off
	global_load_ushort v77, v[110:111], off offset:64
	s_mov_b64 s[100:101], 0x11000
	v_lshl_add_u64 v[110:111], v[108:109], 0, s[100:101]
	global_load_ushort v78, v[110:111], off
	global_load_ushort v79, v[110:111], off offset:64
	s_mov_b64 s[100:101], 0x12000
	v_lshl_add_u64 v[110:111], v[108:109], 0, s[100:101]
	global_load_ushort v80, v[110:111], off
	global_load_ushort v81, v[110:111], off offset:64
	s_mov_b64 s[100:101], 0x13000
	v_lshl_add_u64 v[110:111], v[108:109], 0, s[100:101]
	global_load_ushort v82, v[110:111], off
	global_load_ushort v83, v[110:111], off offset:64
	s_mov_b64 s[100:101], 0x18000
	v_lshl_add_u64 v[110:111], v[108:109], 0, s[100:101]
	global_load_ushort v84, v[110:111], off
	global_load_ushort v85, v[110:111], off offset:64
	s_mov_b64 s[100:101], 0x19000
	v_lshl_add_u64 v[110:111], v[108:109], 0, s[100:101]
	global_load_ushort v86, v[110:111], off
	global_load_ushort v87, v[110:111], off offset:64
	s_mov_b64 s[100:101], 0x1a000
	v_lshl_add_u64 v[110:111], v[108:109], 0, s[100:101]
	global_load_ushort v88, v[110:111], off
	global_load_ushort v89, v[110:111], off offset:64
	s_mov_b64 s[100:101], 0x1b000
	v_lshl_add_u64 v[110:111], v[108:109], 0, s[100:101]
	global_load_ushort v90, v[110:111], off
	global_load_ushort v91, v[110:111], off offset:64
	s_waitcnt vmcnt(30)
	v_mov_b64_e32 v[34:35], v[92:93]
	v_mov_b64_e32 v[36:37], v[94:95]
	v_mov_b32_e32 v46, v60
	v_add_f32_e32 v18, v18, v34
	s_waitcnt vmcnt(30)
	v_mov_b32_e32 v44, v61
	v_lshlrev_b32_e32 v46, 16, v46
	v_add_f32_e32 v2, v2, v34
	v_mul_f32_e32 v18, v18, v46
	v_cvt_pk_bf16_f32 v18, v18, v18
	v_add_f32_e32 v4, v4, v36
	s_nop 0
	v_lshlrev_b32_e32 v47, 16, v44
	v_lshlrev_b64 v[44:45], 11, v[42:43]
	v_lshl_add_u64 v[44:45], v[38:39], 0, v[44:45]
	v_mul_f32_e32 v2, v2, v47
	global_store_short v[44:45], v18, off
	v_cvt_pk_bf16_f32 v2, v2, v2
	global_store_short v[44:45], v2, off offset:64
	v_or_b32_e32 v44, 1, v42
	v_ashrrev_i32_e32 v45, 31, v44
	v_lshlrev_b64 v[46:47], 12, v[44:45]
	v_lshl_add_u64 v[46:47], v[40:41], 0, v[46:47]
	s_waitcnt vmcnt(28)
	v_mov_b32_e32 v2, v62
	v_mov_b32_e32 v18, v63
	v_lshlrev_b32_e32 v2, 16, v2
	s_nop 0
	v_lshlrev_b32_e32 v34, 16, v18
	v_add_f32_e32 v18, v19, v35
	v_mul_f32_e32 v2, v18, v2
	v_lshlrev_b64 v[18:19], 11, v[44:45]
	v_cvt_pk_bf16_f32 v2, v2, v2
	v_lshl_add_u64 v[18:19], v[38:39], 0, v[18:19]
	global_store_short v[18:19], v2, off
	v_add_f32_e32 v2, v3, v35
	v_mul_f32_e32 v2, v2, v34
	v_cvt_pk_bf16_f32 v2, v2, v2
	global_store_short v[18:19], v2, off offset:64
	v_or_b32_e32 v2, 2, v42
	v_ashrrev_i32_e32 v3, 31, v2
	v_lshlrev_b64 v[18:19], 12, v[2:3]
	v_lshl_add_u64 v[18:19], v[40:41], 0, v[18:19]
	v_lshlrev_b64 v[2:3], 11, v[2:3]
	v_add_f32_e32 v19, v20, v36
	v_lshl_add_u64 v[2:3], v[38:39], 0, v[2:3]
	s_waitcnt vmcnt(26)
	v_mov_b32_e32 v34, v64
	v_mov_b32_e32 v18, v65
	v_lshlrev_b32_e32 v34, 16, v34
	v_mul_f32_e32 v19, v19, v34
	s_nop 0
	v_lshlrev_b32_e32 v18, 16, v18
	v_mul_f32_e32 v4, v4, v18
	v_cvt_pk_bf16_f32 v19, v19, v19
	global_store_short v[2:3], v19, off
	v_cvt_pk_bf16_f32 v4, v4, v4
	global_store_short v[2:3], v4, off offset:64
	v_or_b32_e32 v2, 3, v42
	v_ashrrev_i32_e32 v3, 31, v2
	v_lshlrev_b64 v[18:19], 12, v[2:3]
	v_lshl_add_u64 v[18:19], v[40:41], 0, v[18:19]
	v_lshlrev_b64 v[2:3], 11, v[2:3]
	v_add_f32_e32 v19, v21, v37
	v_lshl_add_u64 v[2:3], v[38:39], 0, v[2:3]
	s_waitcnt vmcnt(24)
	v_mov_b32_e32 v4, v66
	v_mov_b32_e32 v18, v67
	v_lshlrev_b32_e32 v4, 16, v4
	v_mul_f32_e32 v4, v19, v4
	v_cvt_pk_bf16_f32 v4, v4, v4
	s_nop 0
	v_lshlrev_b32_e32 v18, 16, v18
	global_store_short v[2:3], v4, off
	v_add_f32_e32 v4, v5, v37
	v_mul_f32_e32 v4, v4, v18
	v_or_b32_e32 v18, 8, v42
	v_ashrrev_i32_e32 v19, 31, v18
	v_lshlrev_b64 v[20:21], 12, v[18:19]
	v_cvt_pk_bf16_f32 v4, v4, v4
	global_store_short v[2:3], v4, off offset:64
	v_lshl_add_u64 v[20:21], v[40:41], 0, v[20:21]
	v_lshlrev_b64 v[18:19], 11, v[18:19]
	v_lshl_add_u64 v[18:19], v[38:39], 0, v[18:19]
	s_waitcnt vmcnt(22)
	v_mov_b64_e32 v[2:3], v[96:97]
	v_mov_b64_e32 v[4:5], v[98:99]
	v_mov_b32_e32 v34, v68
	v_mov_b32_e32 v20, v69
	v_add_f32_e32 v21, v22, v2
	s_nop 0
	v_lshlrev_b32_e32 v34, 16, v34
	v_add_f32_e32 v2, v6, v2
	s_nop 0
	v_lshlrev_b32_e32 v20, 16, v20
	v_mul_f32_e32 v21, v21, v34
	v_mul_f32_e32 v2, v2, v20
	v_cvt_pk_bf16_f32 v21, v21, v21
	global_store_short v[18:19], v21, off
	v_cvt_pk_bf16_f32 v2, v2, v2
	global_store_short v[18:19], v2, off offset:64
	v_or_b32_e32 v18, 9, v42
	v_ashrrev_i32_e32 v19, 31, v18
	v_lshlrev_b64 v[20:21], 12, v[18:19]
	v_lshl_add_u64 v[20:21], v[40:41], 0, v[20:21]
	v_add_f32_e32 v20, v23, v3
	v_lshlrev_b64 v[18:19], 11, v[18:19]
	v_lshl_add_u64 v[18:19], v[38:39], 0, v[18:19]
	s_waitcnt vmcnt(20)
	v_mov_b32_e32 v2, v70
	v_mov_b32_e32 v6, v71
	v_lshlrev_b32_e32 v2, 16, v2
	v_mul_f32_e32 v2, v20, v2
	v_cvt_pk_bf16_f32 v2, v2, v2
	s_nop 0
	v_lshlrev_b32_e32 v6, 16, v6
	global_store_short v[18:19], v2, off
	v_add_f32_e32 v2, v7, v3
	v_mul_f32_e32 v2, v2, v6
	v_cvt_pk_bf16_f32 v2, v2, v2
	global_store_short v[18:19], v2, off offset:64
	v_or_b32_e32 v2, 10, v42
	v_ashrrev_i32_e32 v3, 31, v2
	v_lshlrev_b64 v[6:7], 12, v[2:3]
	v_lshl_add_u64 v[6:7], v[40:41], 0, v[6:7]
	v_lshlrev_b64 v[2:3], 11, v[2:3]
	v_add_f32_e32 v7, v24, v4
	v_add_f32_e32 v4, v8, v4
	v_lshl_add_u64 v[2:3], v[38:39], 0, v[2:3]
	s_waitcnt vmcnt(18)
; __device__ __forceinline__ unsigned f2bf(float f) { return pk2(f, f) & 0xffffu; }
; __device__ __forceinline__ void gmlp_unit2(const PT& a, int l, int u, LAS unsigned char* lds) {
;     ...
; #pragma unroll
;     for (int r = 0; r < 16; ++r) { const int p = pt_ * 32 + (r & 3) + 8 * (r >> 2) + 4 * hh; const float bb = bs[p];
;         const size_t o = (size_t)(tok0 + p) * 2048 + g * 128 + dt0 * 32 + n;
;         const float u0 = bf2f(PA[o]), u1 = bf2f(PA[o + 32]);
;         const size_t oy = (size_t)(tok0 + p) * 1024 + g * 128 + dt0 * 32 + n;
;         YA[oy] = (bf16_t)f2bf(u0 * (acc0[r] + bb)); YA[oy + 32] = (bf16_t)f2bf(u1 * (acc1[r] + bb)); }
	v_mov_b32_e32 v18, v72
	v_mov_b32_e32 v6, v73
	v_lshlrev_b32_e32 v18, 16, v18
	v_mul_f32_e32 v7, v7, v18
	s_nop 0
	v_lshlrev_b32_e32 v6, 16, v6
	v_mul_f32_e32 v4, v4, v6
	v_cvt_pk_bf16_f32 v7, v7, v7
	global_store_short v[2:3], v7, off
	v_cvt_pk_bf16_f32 v4, v4, v4
	global_store_short v[2:3], v4, off offset:64
	v_or_b32_e32 v2, 11, v42
	v_ashrrev_i32_e32 v3, 31, v2
	v_lshlrev_b64 v[6:7], 12, v[2:3]
	v_lshl_add_u64 v[6:7], v[40:41], 0, v[6:7]
	v_lshlrev_b64 v[2:3], 11, v[2:3]
	v_add_f32_e32 v7, v25, v5
	v_lshl_add_u64 v[2:3], v[38:39], 0, v[2:3]
	s_waitcnt vmcnt(16)
	v_mov_b32_e32 v4, v74
	v_mov_b32_e32 v6, v75
	v_lshlrev_b32_e32 v4, 16, v4
	v_mul_f32_e32 v4, v7, v4
	v_cvt_pk_bf16_f32 v4, v4, v4
	s_nop 0
	v_lshlrev_b32_e32 v6, 16, v6
	global_store_short v[2:3], v4, off
	v_add_f32_e32 v4, v9, v5
	v_mul_f32_e32 v4, v4, v6
	v_or_b32_e32 v6, 16, v42
	v_ashrrev_i32_e32 v7, 31, v6
	v_lshlrev_b64 v[8:9], 12, v[6:7]
	v_cvt_pk_bf16_f32 v4, v4, v4
	global_store_short v[2:3], v4, off offset:64
	v_lshl_add_u64 v[8:9], v[40:41], 0, v[8:9]
	v_lshlrev_b64 v[6:7], 11, v[6:7]
	v_lshl_add_u64 v[6:7], v[38:39], 0, v[6:7]
	s_waitcnt vmcnt(14)
	v_mov_b64_e32 v[2:3], v[100:101]
	v_mov_b64_e32 v[4:5], v[102:103]
	v_mov_b32_e32 v18, v76
	v_mov_b32_e32 v8, v77
	v_add_f32_e32 v9, v26, v2
	s_nop 0
	v_lshlrev_b32_e32 v18, 16, v18
	v_add_f32_e32 v2, v10, v2
	s_nop 0
	v_lshlrev_b32_e32 v8, 16, v8
	v_mul_f32_e32 v9, v9, v18
	v_mul_f32_e32 v2, v2, v8
	v_cvt_pk_bf16_f32 v9, v9, v9
	global_store_short v[6:7], v9, off
	v_cvt_pk_bf16_f32 v2, v2, v2
	global_store_short v[6:7], v2, off offset:64
	v_or_b32_e32 v6, 17, v42
	v_ashrrev_i32_e32 v7, 31, v6
	v_lshlrev_b64 v[8:9], 12, v[6:7]
	v_lshl_add_u64 v[8:9], v[40:41], 0, v[8:9]
	v_lshlrev_b64 v[6:7], 11, v[6:7]
	v_add_f32_e32 v9, v27, v3
	v_lshl_add_u64 v[6:7], v[38:39], 0, v[6:7]
	s_waitcnt vmcnt(12)
	v_mov_b32_e32 v2, v78
	v_mov_b32_e32 v8, v79
	v_lshlrev_b32_e32 v2, 16, v2
	v_mul_f32_e32 v2, v9, v2
	v_cvt_pk_bf16_f32 v2, v2, v2
	s_nop 0
	v_lshlrev_b32_e32 v8, 16, v8
	global_store_short v[6:7], v2, off
	v_add_f32_e32 v2, v11, v3
	v_mul_f32_e32 v2, v2, v8
	v_cvt_pk_bf16_f32 v2, v2, v2
	global_store_short v[6:7], v2, off offset:64
	v_or_b32_e32 v2, 18, v42
	v_ashrrev_i32_e32 v3, 31, v2
	v_lshlrev_b64 v[6:7], 12, v[2:3]
	v_lshl_add_u64 v[6:7], v[40:41], 0, v[6:7]
	v_lshlrev_b64 v[2:3], 11, v[2:3]
	v_add_f32_e32 v7, v28, v4
	v_add_f32_e32 v4, v12, v4
	v_lshl_add_u64 v[2:3], v[38:39], 0, v[2:3]
	s_waitcnt vmcnt(10)
	v_mov_b32_e32 v8, v80
	v_mov_b32_e32 v6, v81
	v_lshlrev_b32_e32 v8, 16, v8
	v_mul_f32_e32 v7, v7, v8
	s_nop 0
	v_lshlrev_b32_e32 v6, 16, v6
	v_mul_f32_e32 v4, v4, v6
	v_cvt_pk_bf16_f32 v7, v7, v7
	global_store_short v[2:3], v7, off
	v_cvt_pk_bf16_f32 v4, v4, v4
	global_store_short v[2:3], v4, off offset:64
	v_or_b32_e32 v2, 19, v42
	v_ashrrev_i32_e32 v3, 31, v2
	v_lshlrev_b64 v[6:7], 12, v[2:3]
	v_lshl_add_u64 v[6:7], v[40:41], 0, v[6:7]
	v_lshlrev_b64 v[2:3], 11, v[2:3]
	v_add_f32_e32 v7, v29, v5
	v_lshl_add_u64 v[2:3], v[38:39], 0, v[2:3]
	s_waitcnt vmcnt(8)
	v_mov_b32_e32 v4, v82
	v_mov_b32_e32 v6, v83
	v_lshlrev_b32_e32 v4, 16, v4
	v_mul_f32_e32 v4, v7, v4
	v_cvt_pk_bf16_f32 v4, v4, v4
	s_nop 0
	v_lshlrev_b32_e32 v6, 16, v6
	global_store_short v[2:3], v4, off
	v_add_f32_e32 v4, v13, v5
	v_mul_f32_e32 v4, v4, v6
	v_or_b32_e32 v6, 24, v42
	v_ashrrev_i32_e32 v7, 31, v6
	v_lshlrev_b64 v[8:9], 12, v[6:7]
	v_cvt_pk_bf16_f32 v4, v4, v4
	global_store_short v[2:3], v4, off offset:64
	v_lshl_add_u64 v[8:9], v[40:41], 0, v[8:9]
	v_lshlrev_b64 v[6:7], 11, v[6:7]
	v_lshl_add_u64 v[6:7], v[38:39], 0, v[6:7]
	v_readlane_b32 s0, v253, 40
	s_add_i32 s2, s2, s0
	s_cmpk_gt_i32 s2, 0x1ff
	s_waitcnt vmcnt(6)
	v_mov_b64_e32 v[2:3], v[104:105]
	v_mov_b64_e32 v[4:5], v[106:107]
	v_mov_b32_e32 v1, v84
	v_mov_b32_e32 v8, v85
	v_add_f32_e32 v9, v30, v2
	s_nop 0
	v_lshlrev_b32_e32 v1, 16, v1
	v_mul_f32_e32 v1, v9, v1
	v_cvt_pk_bf16_f32 v1, v1, v1
	s_nop 0
	v_lshlrev_b32_e32 v8, 16, v8
	global_store_short v[6:7], v1, off
	v_add_f32_e32 v1, v14, v2
	v_mul_f32_e32 v1, v1, v8
	v_cvt_pk_bf16_f32 v1, v1, v1
	global_store_short v[6:7], v1, off offset:64
	v_or_b32_e32 v6, 25, v42
	v_ashrrev_i32_e32 v7, 31, v6
	v_lshlrev_b64 v[8:9], 12, v[6:7]
	v_lshl_add_u64 v[8:9], v[40:41], 0, v[8:9]
	v_add_f32_e32 v8, v31, v3
	v_lshlrev_b64 v[6:7], 11, v[6:7]
	v_lshl_add_u64 v[6:7], v[38:39], 0, v[6:7]
	s_waitcnt vmcnt(4)
	v_mov_b32_e32 v1, v86
	v_mov_b32_e32 v2, v87
	v_lshlrev_b32_e32 v1, 16, v1
	v_mul_f32_e32 v1, v8, v1
	v_cvt_pk_bf16_f32 v1, v1, v1
	s_nop 0
	v_lshlrev_b32_e32 v2, 16, v2
	global_store_short v[6:7], v1, off
	v_add_f32_e32 v1, v15, v3
	v_mul_f32_e32 v1, v1, v2
	v_or_b32_e32 v2, 26, v42
	v_ashrrev_i32_e32 v3, 31, v2
	v_cvt_pk_bf16_f32 v1, v1, v1
	global_store_short v[6:7], v1, off offset:64
	v_lshlrev_b64 v[6:7], 12, v[2:3]
	v_lshl_add_u64 v[6:7], v[40:41], 0, v[6:7]
	v_lshlrev_b64 v[2:3], 11, v[2:3]
	v_add_f32_e32 v7, v32, v4
	v_lshl_add_u64 v[2:3], v[38:39], 0, v[2:3]
	s_waitcnt vmcnt(2)
	v_mov_b32_e32 v1, v88
	v_mov_b32_e32 v6, v89
	v_lshlrev_b32_e32 v1, 16, v1
	v_mul_f32_e32 v1, v7, v1
	v_cvt_pk_bf16_f32 v1, v1, v1
	s_nop 0
	v_lshlrev_b32_e32 v6, 16, v6
	global_store_short v[2:3], v1, off
	v_add_f32_e32 v1, v16, v4
	v_mul_f32_e32 v1, v1, v6
	v_cvt_pk_bf16_f32 v1, v1, v1
	global_store_short v[2:3], v1, off offset:64
	v_or_b32_e32 v2, 27, v42
	v_ashrrev_i32_e32 v3, 31, v2
	v_lshlrev_b64 v[6:7], 12, v[2:3]
	v_lshl_add_u64 v[6:7], v[40:41], 0, v[6:7]
	v_add_f32_e32 v6, v33, v5
	v_lshlrev_b64 v[2:3], 11, v[2:3]
	v_lshl_add_u64 v[2:3], v[38:39], 0, v[2:3]
	s_waitcnt vmcnt(0)
	v_mov_b32_e32 v1, v90
	v_mov_b32_e32 v4, v91
	v_lshlrev_b32_e32 v1, 16, v1
	v_mul_f32_e32 v1, v6, v1
	v_cvt_pk_bf16_f32 v1, v1, v1
	s_nop 0
	v_lshlrev_b32_e32 v4, 16, v4
	global_store_short v[2:3], v1, off
	v_add_f32_e32 v1, v17, v5
	v_mul_f32_e32 v1, v1, v4
	v_cvt_pk_bf16_f32 v1, v1, v1
	global_store_short v[2:3], v1, off offset:64
	s_cbranch_scc1 .LBB0_1203

; __device__ __forceinline__ int opaque_tid() { int t = threadIdx.x; asm volatile("" : "+v"(t)); return t; }
;     for (int it = 0; it < budget; ++it) {
;         unsigned r = 0; if (lane == 0) r = __hip_atomic_fetch_add(ctr, 2u, __ATOMIC_RELAXED, __HIP_MEMORY_SCOPE_AGENT);
;         r = (unsigned)__builtin_amdgcn_readfirstlane((int)r) + (unsigned)CV_PRO_ITEMS;
;         if (r >= (unsigned)IT_LAYER) break;
;         cv_pair(a, lds, l, (int)r, wave, lane);
;     }
; }
; __global__ void __launch_bounds__(NTHREADS, 2) mk_fwd(Args args) {
;     ...
;             if (l + 1 < DEPTH && !(G >= 256 && bid < 128)) { __syncthreads(); const int tid_ = opaque_tid(); convert_layer_queue(pt, lds, l + 1, cvq, tid_ >> 6, tid_ & 63); }
.LBB0_1377:
	s_cmp_eq_u32 s64, 3
	v_readlane_b32 s2, v253, 61
	s_cselect_b64 s[0:1], -1, 0
	v_readlane_b32 s3, v253, 62
	s_or_b64 s[0:1], s[2:3], s[0:1]
	v_readlane_b32 s2, v252, 4
	s_cmp_lg_u32 s2, 0x100
	s_cselect_b64 s[2:3], -1, 0
	s_or_b64 s[0:1], s[0:1], s[2:3]
	v_readlane_b32 s28, v254, 55
	s_mov_b32 s36, s64
	s_and_b64 vcc, exec, s[0:1]
	v_readlane_b32 s29, v254, 56
	s_cbranch_vccnz .LBB0_1470
	v_readlane_b32 s0, v254, 53
	v_readlane_b32 s1, v254, 54
	s_mov_b32 s3, s1
	s_lshl_b32 s2, s36, 6
	s_lshl_b64 s[0:1], s[2:3], 2
	v_readlane_b32 s4, v254, 60
	v_readlane_b32 s5, v254, 61
	s_add_u32 s0, s4, s0
	s_addc_u32 s1, s5, s1
	s_add_u32 s0, s0, 0x8000
	s_addc_u32 s1, s1, 0
	s_add_i32 s2, s36, 1
	s_mul_hi_u32 s33, s2, 0x2c00000
	s_mul_i32 s34, s2, 0x2c00000
	s_mul_hi_u32 s35, s2, 0x1600000
	s_mul_i32 s50, s2, 0x1600000
	s_lshl_b32 s6, s2, 11
	s_mov_b32 s7, s3
	s_lshl_b64 s[8:9], s[2:3], 24
	s_lshl_b64 s[10:11], s[2:3], 23
	s_mul_hi_u32 s51, s2, 0xc00000
	s_mul_i32 s52, s2, 0xc00000
	s_mul_hi_u32 s53, s2, 0x7280000
	s_mul_i32 s54, s2, 0x7280000
	s_mul_hi_u32 s55, s2, 0x3a00000
	v_writelane_b32 v254, s2, 53
	v_mov_b32_e32 v2, v0
	s_mul_i32 s56, s2, 0x3a00000
	v_writelane_b32 v254, s3, 54
	s_waitcnt vmcnt(0) lgkmcnt(0)
	s_barrier
	s_movk_i32 s2, 0x4200
	v_lshrrev_b32_e32 v1, 6, v2
	v_and_b32_e32 v3, 63, v2
	v_readfirstlane_b32 s100, v1
	v_readlane_b32 s101, v252, 0
	s_sub_u32 s101, s101, 128
	s_lshl_b32 s101, s101, 3
	s_add_u32 s100, s100, s101
	s_lshl_b32 s100, s100, 1
	s_add_u32 s100, s100, 0x1800
	v_mul_lo_u32 v1, v1, s2
	v_cmp_eq_u32_e64 s[40:41], 0, v3
	v_add_u32_e32 v3, 0, v1
	v_lshlrev_b32_e32 v1, 2, v2
	v_and_b32_e32 v66, 28, v1
	v_bfe_u32 v1, v2, 3, 3
	v_lshlrev_b32_e32 v2, 3, v2
	v_and_b32_e32 v68, 56, v2
	v_lshl_add_u32 v4, v66, 2, v3
	v_mul_u32_u24_e32 v5, 0x84, v1
	v_mul_u32_u24_e32 v2, 0x84, v68
	v_lshlrev_b32_e32 v6, 2, v1
	v_or_b32_e32 v67, 8, v1
	v_or_b32_e32 v69, 16, v1
	v_or_b32_e32 v71, 24, v1
	v_or_b32_e32 v73, 32, v1
	v_or_b32_e32 v75, 40, v1
	v_or_b32_e32 v77, 48, v1
	v_or_b32_e32 v79, 56, v1
	v_add3_u32 v81, v3, v2, v6
	s_mov_b32 s57, 0x3
	v_add_u32_e32 v83, v4, v5
	s_branch .LBB0_1381

;     __device__ __forceinline__ const float* in(int i) const { return (const float*)(const GAS float*)raw(i); }
;     __device__ __forceinline__ unsigned char* ws() const { return (unsigned char*)(GAS unsigned char*)raw(N_INPUTS + 1); }
; __device__ __forceinline__ CvItem cv_decode(const PT& a, int l, int r) {
;     unsigned char* ws = a.ws(); CvItem it;
;     if (r < IT_WIN) { const int kb = r / 458, nb = r % 458, n0 = nb * 32;
;         int drow; if (n0 < 2048) drow = n0; else if (n0 < 5120) drow = NIN_MAIN + (n0 - 2048); else if (n0 < 8512) drow = 2048 + (n0 - 5120); else drow = 5632 + (n0 - 8512);
;         it = CvItem{a.in(I_W_IN) + (size_t)l * D * NIN, NIN, kb * 64, n0, (bf16_t*)(ws + WS_WIN + l * WIN_L), D, drow, a.in(I_NORM_MIX_G) + l * D}; return it; }
;     r -= IT_WIN;
;     if (r < 3 * IT_BR) { const int br = r / IT_BR; r -= br * IT_BR; const int kb = r / 64, nb = r % 64;
;         it = CvItem{a.in(br == 0 ? I_W_BR_A : (br == 1 ? I_W_BR_B : I_W_BR_C)) + (size_t)l * 1024 * D, D, kb * 64, nb * 32, (bf16_t*)(ws + WS_WBR + l * WBR_L) + (size_t)br * D * 1024, 1024, nb * 32, nullptr}; return it; }
;     r -= 3 * IT_BR;
;     if (r < IT_OUT) { const int kb = r / 64, nb = r % 64;
;         it = CvItem{a.in(I_W_OUT) + (size_t)l * D * D, D, kb * 64, nb * 32, (bf16_t*)(ws + WS_WOUT + l * WOUT_L), D, nb * 32, nullptr}; return it; }
;     r -= IT_OUT;
;     if (r < 2 * IT_GU) { const int up = r / IT_GU; r -= up * IT_GU; const int kb = r / 176, nb = r % 176, n0 = nb * 32;
;         it = CvItem{a.in(up ? I_W_FFN_UP : I_W_FFN_GATE) + (size_t)l * D * DFF, DFF, kb * 64, n0, (bf16_t*)(ws + WS_WGU + l * WGU_L), D, 256 * (n0 / 128) + (n0 % 128) + 128 * up, a.in(I_NORM_FFN_G) + l * D}; return it; }
;     r -= 2 * IT_GU;
;     { const int kb = r / 64, nb = r % 64;
;       it = CvItem{a.in(I_W_FFN_DOWN) + (size_t)l * DFF * D, D, kb * 64, nb * 32, (bf16_t*)(ws + WS_WDN + l * WDN_L), DFF, nb * 32, nullptr}; }
;     for (int it = 0; it < budget; ++it) {
;         unsigned r = 0; if (lane == 0) r = __hip_atomic_fetch_add(ctr, 2u, __ATOMIC_RELAXED, __HIP_MEMORY_SCOPE_AGENT);
;         r = (unsigned)__builtin_amdgcn_readfirstlane((int)r) + (unsigned)CV_PRO_ITEMS;
;         if (r >= (unsigned)IT_LAYER) break;
;         cv_pair(a, lds, l, (int)r, wave, lane);
.LBB0_1381:
	s_mov_b32 s24, s100
	s_add_u32 s100, s100, 0x800
	s_add_i32 s24, s24, 0xffffc800
	s_cmp_lt_u32 s24, 0xffff70c0
	s_mov_b64 s[2:3], -1
	s_cbranch_scc1 .LBB0_1380
	v_mov_b32_e32 v2, 0x23a60
	s_add_i32 s15, s24, 0x8f40
	v_add_u32_e32 v2, 0, v2
	ds_read_b64 v[2:3], v2
	s_cmpk_gt_u32 s15, 0x393f
	s_waitcnt lgkmcnt(0)
	v_readfirstlane_b32 s20, v3
	v_readfirstlane_b32 s21, v2
	s_cbranch_scc0 .LBB0_1399
	s_cmpk_gt_u32 s15, 0x453f
	s_cbranch_scc0 .LBB0_1396
	s_cmpk_gt_u32 s15, 0x4d3f
	s_mov_b64 s[18:19], -1
	s_cbranch_scc0 .LBB0_1393
	s_cmpk_gt_u32 s15, 0x793f
	s_cbranch_scc0 .LBB0_1391
	v_mov_b32_e32 v2, 0x23a48
	s_and_b32 s2, s15, 0x7fffffc0
	v_add_u32_e32 v2, 0, v2
	ds_read_b64 v[2:3], v2
	s_add_i32 s14, s2, 0xffff86c0
	s_waitcnt lgkmcnt(0)
	v_readfirstlane_b32 s3, v2
	v_readfirstlane_b32 s2, v3
	s_add_u32 s30, s3, s34
	s_addc_u32 s31, s2, s33
	s_lshl_b32 s2, s15, 5
	s_and_b32 s25, s2, 0x7e0
	s_add_u32 s2, s21, s50
	s_addc_u32 s3, s20, s35
	s_add_u32 s12, s2, 0x1ea00000
	s_addc_u32 s13, s3, 0
	s_mov_b64 s[2:3], 0

; __device__ __forceinline__ int opaque_tid() { int t = threadIdx.x; asm volatile("" : "+v"(t)); return t; }
;     for (int it = 0; it < budget; ++it) {
;         unsigned r = 0; if (lane == 0) r = __hip_atomic_fetch_add(ctr, 2u, __ATOMIC_RELAXED, __HIP_MEMORY_SCOPE_AGENT);
;         r = (unsigned)__builtin_amdgcn_readfirstlane((int)r) + (unsigned)CV_PRO_ITEMS;
;         if (r >= (unsigned)IT_LAYER) break;
;         cv_pair(a, lds, l, (int)r, wave, lane);
;     }
; }
; __global__ void __launch_bounds__(NTHREADS, 2) mk_fwd(Args args) {
;     ...
;             if (l + 1 < DEPTH && !(G >= 256 && bid < 128)) { __syncthreads(); const int tid_ = opaque_tid(); convert_layer_queue(pt, lds, l + 1, cvq, tid_ >> 6, tid_ & 63); }
.LBB0_1843:
	v_readlane_b32 s2, v252, 4
	s_cmp_lg_u32 s2, 0x100
	s_cbranch_scc1 .LcvqB_skip
	v_readlane_b32 s2, v252, 0
	s_cmp_lt_u32 s2, 128
	s_cbranch_scc1 .LcvqB_skip
	s_cmp_gt_u32 s36, 2
	s_cbranch_scc1 .LcvqB_skip
	v_writelane_b32 v255, s0, 8
	v_writelane_b32 v255, s1, 9
	v_writelane_b32 v255, s40, 10
	v_writelane_b32 v255, s41, 11
	s_mov_b32 s64, s36
	v_readlane_b32 s0, v254, 53
	v_readlane_b32 s1, v254, 54
	s_mov_b32 s3, s1
	s_lshl_b32 s2, s36, 6
	s_lshl_b64 s[0:1], s[2:3], 2
	v_readlane_b32 s4, v254, 60
	v_readlane_b32 s5, v254, 61
	s_add_u32 s0, s4, s0
	s_addc_u32 s1, s5, s1
	s_add_u32 s0, s0, 0x8000
	s_addc_u32 s1, s1, 0
	s_add_i32 s2, s36, 1
	s_mul_hi_u32 s33, s2, 0x2c00000
	s_mul_i32 s34, s2, 0x2c00000
	s_mul_hi_u32 s35, s2, 0x1600000
	s_mul_i32 s50, s2, 0x1600000
	s_lshl_b32 s6, s2, 11
	s_mov_b32 s7, s3
	s_lshl_b64 s[8:9], s[2:3], 24
	s_lshl_b64 s[10:11], s[2:3], 23
	s_mul_hi_u32 s51, s2, 0xc00000
	s_mul_i32 s52, s2, 0xc00000
	s_mul_hi_u32 s53, s2, 0x7280000
	s_mul_i32 s54, s2, 0x7280000
	s_mul_hi_u32 s55, s2, 0x3a00000
	v_writelane_b32 v254, s2, 53
	v_mov_b32_e32 v2, v0
	s_mul_i32 s56, s2, 0x3a00000
	v_writelane_b32 v254, s3, 54
	s_waitcnt vmcnt(0) lgkmcnt(0)
	s_barrier
	s_movk_i32 s2, 0x4200
	v_lshrrev_b32_e32 v1, 6, v2
	v_and_b32_e32 v3, 63, v2
	v_readfirstlane_b32 s100, v1
	v_readlane_b32 s101, v252, 0
	s_sub_u32 s101, s101, 128
	s_lshl_b32 s101, s101, 3
	s_add_u32 s100, s100, s101
	s_lshl_b32 s100, s100, 1
	s_add_u32 s100, s100, 0x3000
	v_mul_lo_u32 v1, v1, s2
	v_cmp_eq_u32_e64 s[40:41], 0, v3
	v_add_u32_e32 v3, 0, v1
	v_lshlrev_b32_e32 v1, 2, v2
	v_and_b32_e32 v66, 28, v1
	v_bfe_u32 v1, v2, 3, 3
	v_lshlrev_b32_e32 v2, 3, v2
	v_and_b32_e32 v68, 56, v2
	v_lshl_add_u32 v4, v66, 2, v3
	v_mul_u32_u24_e32 v5, 0x84, v1
	v_mul_u32_u24_e32 v2, 0x84, v68
	v_lshlrev_b32_e32 v6, 2, v1
	v_or_b32_e32 v67, 8, v1
	v_or_b32_e32 v69, 16, v1
	v_or_b32_e32 v71, 24, v1
	v_or_b32_e32 v73, 32, v1
	v_or_b32_e32 v75, 40, v1
	v_or_b32_e32 v77, 48, v1
	v_or_b32_e32 v79, 56, v1
	v_add3_u32 v81, v3, v2, v6
	s_mov_b32 s57, 0x1
	v_add_u32_e32 v83, v4, v5
	s_branch .LcvqB_1381
